# retention mixer: stage-2 St*q MFMA group moved ahead of the P barrier
# baseline (speedup 1.0000x reference)
; template <int DK, bool IS_A, int NDV>
; __device__ __forceinline__ void mix_stream(const Params& p, LAS unsigned char* lds, int l, int rs, int T, int h, int dir, int dvh) {
;     ...
;         { const int tt = w >> 1, ts0 = (w & 1) * 2; f32x4 pa = (f32x4){0.f, 0.f, 0.f, 0.f}, pb = pa;
;           bf16x8 gq_[KS], gk0[KS], gk1[KS];
; #pragma unroll
;           for (int ks = 0; ks < KS; ++ks) { gq_[ks] = ldfrag(Qs, QP, tt, ks, fr, fqx); gk0[ks] = ldfrag(Ks, QP, ts0, ks, fr, fqx); gk1[ks] = ldfrag(Ks, QP, ts0 + 1, ks, fr, fqx); }
;           __builtin_amdgcn_sched_barrier(0);
; #pragma unroll
;           for (int ks = 0; ks < KS; ++ks) { pa = MFMA16(gk0[ks], gq_[ks], pa); pb = MFMA16(gk1[ks], gq_[ks], pb); }
;           const int t = tt * 16 + fr, s0 = ts0 * 16 + fq * 4, s1 = s0 + 16;
;           u32x2 w0, w1;
;           w0.x = cvt_pk_bf16(t >= s0 ? pa[0] : 0.f, t >= s0 + 1 ? pa[1] : 0.f); w0.y = cvt_pk_bf16(t >= s0 + 2 ? pa[2] : 0.f, t >= s0 + 3 ? pa[3] : 0.f);
;           w1.x = cvt_pk_bf16(t >= s1 ? pb[0] : 0.f, t >= s1 + 1 ? pb[1] : 0.f); w1.y = cvt_pk_bf16(t >= s1 + 2 ? pb[2] : 0.f, t >= s1 + 3 ? pb[3] : 0.f);
;           *(LAS u32x2*)(Ps + t * TP + ((s0 * 2) ^ (gx << 4))) = w0; *(LAS u32x2*)(Ps + t * TP + ((s1 * 2) ^ (gx << 4))) = w1; }
; #pragma unroll
;         for (int ks = 0; ks < 2; ++ks) { bf16x8 ak[2], bv[DVW];
; #pragma unroll
;             for (int dki = 0; dki < 2; ++dki) ak[dki] = ldfrag(Kt, TP, tdk0 + dki, ks, fr, fqx);
; #pragma unroll
;             for (int dvi = 0; dvi < DVW; ++dvi) bv[dvi] = ldfrag(Vt, TP, tdv0 + dvi, ks, fr, fqx);
;             __builtin_amdgcn_sched_barrier(0);
; #pragma unroll
;             for (int dki = 0; dki < 2; ++dki)
; #pragma unroll
;                 for (int dvi = 0; dvi < DVW; ++dvi) U[dki * DVW + dvi] = MFMA16(ak[dki], bv[dvi], U[dki * DVW + dvi]);
;             __builtin_amdgcn_sched_barrier(0); }
;     ...
;         { const int tp = w >> 2, dp = w & 3; f32x4 o[4];
; #pragma unroll
;           for (int q = 0; q < 4; ++q) o[q] = (f32x4){0.f, 0.f, 0.f, 0.f};
; #pragma unroll
;           for (int kb = 0; kb < KS; kb += 2) { bf16x8 b[2][2], a[2][2];
; #pragma unroll
;               for (int k2 = 0; k2 < 2; ++k2)
; #pragma unroll
;                   for (int i2 = 0; i2 < 2; ++i2) { b[k2][i2] = ldfrag(Qs, QP, 2 * tp + i2, kb + k2, fr, fqx); a[k2][i2] = ldfrag(St, QP, 2 * dp + i2, kb + k2, fr, fqx); }
.LBB0_164:
	s_waitcnt lgkmcnt(0)
	s_barrier
	ds_read_b128 v[106:109], v85
	ds_read_b128 v[110:113], v85 offset:64
	ds_read_b128 v[114:117], v86 offset:9216
	ds_read_b128 v[118:121], v86 offset:9280
	ds_read_b128 v[122:125], v87 offset:9216
	ds_read_b128 v[126:129], v87 offset:9280
	ds_read_b128 v[180:183], v102 offset:36864
	ds_read_b128 v[184:187], v103 offset:36864
	ds_read_b128 v[188:191], v95 offset:18432
	ds_read_b128 v[192:195], v95 offset:20736
	ds_read_b128 v[196:199], v102 offset:36928
	ds_read_b128 v[200:203], v103 offset:36928
	ds_read_b128 v[204:207], v95 offset:18496
	ds_read_b128 v[208:211], v95 offset:20800
	s_waitcnt lgkmcnt(11)
	v_mfma_f32_16x16x32_bf16 v[212:215], v[114:117], v[106:109], 0
	s_waitcnt lgkmcnt(9)
	v_mfma_f32_16x16x32_bf16 v[216:219], v[122:125], v[106:109], 0
	v_mfma_f32_16x16x32_bf16 v[212:215], v[118:121], v[110:113], v[212:215]
	s_waitcnt lgkmcnt(8)
	v_mfma_f32_16x16x32_bf16 v[216:219], v[126:129], v[110:113], v[216:219]
	s_waitcnt lgkmcnt(5)
	v_mfma_f32_16x16x32_bf16 v[122:125], v[180:183], v[188:191], 0
	s_waitcnt lgkmcnt(4)
	v_mfma_f32_16x16x32_bf16 v[106:109], v[180:183], v[192:195], 0
	v_mfma_f32_16x16x32_bf16 v[114:117], v[184:187], v[188:191], 0
	v_mfma_f32_16x16x32_bf16 v[110:113], v[184:187], v[192:195], 0
	s_waitcnt lgkmcnt(1)
	v_mfma_f32_16x16x32_bf16 v[122:125], v[196:199], v[204:207], v[122:125]
	s_waitcnt lgkmcnt(0)
	v_mfma_f32_16x16x32_bf16 v[106:109], v[196:199], v[208:211], v[106:109]
	v_mfma_f32_16x16x32_bf16 v[114:117], v[200:203], v[204:207], v[114:117]
	v_mfma_f32_16x16x32_bf16 v[110:113], v[200:203], v[208:211], v[110:113]
	ds_read_b128 v[118:121], v97
	ds_read_b128 v[126:129], v97 offset:64
	ds_read_b128 v[130:133], v104 offset:46080
	ds_read_b128 v[134:137], v104 offset:46144
	ds_read_b128 v[138:141], v97 offset:2304
	ds_read_b128 v[142:145], v97 offset:2368
	ds_read_b128 v[146:149], v104 offset:48384
	ds_read_b128 v[150:153], v104 offset:48448
	v_cndmask_b32_e64 v39, v212, 0, s[42:43]
	v_cndmask_b32_e64 v105, 0, v213, s[44:45]
	v_cvt_pk_bf16_f32 v220, v39, v105
	v_cndmask_b32_e64 v39, v214, 0, s[46:47]
	v_cndmask_b32_e64 v105, v215, 0, s[48:49]
	v_cvt_pk_bf16_f32 v221, v39, v105
	v_cndmask_b32_e64 v39, v216, 0, s[50:51]
	v_cndmask_b32_e64 v105, v217, 0, s[52:53]
	v_cvt_pk_bf16_f32 v222, v39, v105
	v_cndmask_b32_e64 v39, v218, 0, s[54:55]
	v_cndmask_b32_e64 v105, v219, 0, s[56:57]
	v_cvt_pk_bf16_f32 v223, v39, v105
	ds_write_b64 v93, v[220:221] offset:64512
	ds_write_b64 v94, v[222:223] offset:64512
	s_waitcnt lgkmcnt(7)
	v_mfma_f32_16x16x32_bf16 v[154:157], v[130:133], v[118:121], 0
	s_waitcnt lgkmcnt(3)
	v_mfma_f32_16x16x32_bf16 v[118:121], v[146:149], v[118:121], 0
	v_mfma_f32_16x16x32_bf16 v[130:133], v[130:133], v[138:141], 0
	v_mfma_f32_16x16x32_bf16 v[138:141], v[146:149], v[138:141], 0
	v_mfma_f32_16x16x32_bf16 v[146:149], v[134:137], v[126:129], v[154:157]
	s_waitcnt lgkmcnt(2)
	v_mfma_f32_16x16x32_bf16 v[118:121], v[150:153], v[126:129], v[118:121]
	v_mfma_f32_16x16x32_bf16 v[126:129], v[134:137], v[142:145], v[130:133]
	v_mfma_f32_16x16x32_bf16 v[130:133], v[150:153], v[142:145], v[138:141]
	s_waitcnt lgkmcnt(0)
	s_barrier
	ds_read_b128 v[134:137], v97 offset:64512
	s_nop 1
	ds_read_b128 v[138:141], v97 offset:64576
	ds_read_b128 v[142:145], v104 offset:18432
	ds_read_b128 v[150:153], v104 offset:18496
	ds_read_b128 v[154:157], v98 offset:64512
	ds_read_b128 v[158:161], v98 offset:64576
	ds_read_b128 v[162:165], v104 offset:20736
	ds_read_b128 v[166:169], v104 offset:20800
	s_waitcnt lgkmcnt(5)
	v_mfma_f32_16x16x32_bf16 v[146:149], v[142:145], v[134:137], v[146:149]
	s_waitcnt lgkmcnt(1)
	v_mfma_f32_16x16x32_bf16 v[118:121], v[162:165], v[134:137], v[118:121]
	v_mfma_f32_16x16x32_bf16 v[126:129], v[142:145], v[154:157], v[126:129]
	v_mfma_f32_16x16x32_bf16 v[130:133], v[162:165], v[154:157], v[130:133]
	v_mfma_f32_16x16x32_bf16 v[134:137], v[150:153], v[138:141], v[146:149]
	s_waitcnt lgkmcnt(0)
	v_mfma_f32_16x16x32_bf16 v[118:121], v[166:169], v[138:141], v[118:121]
	v_mfma_f32_16x16x32_bf16 v[126:129], v[150:153], v[158:161], v[126:129]
	v_mfma_f32_16x16x32_bf16 v[130:133], v[166:169], v[158:161], v[130:133]
	v_cvt_pk_bf16_f32 v118, v118, v119
	v_cvt_pk_bf16_f32 v119, v120, v121
	v_mov_b32_e32 v39, v38
	v_pk_mul_f32 v[108:109], v[34:35], v[108:109]
	v_pk_mul_f32 v[106:107], v[36:37], v[106:107]
	v_cvt_pk_bf16_f32 v134, v134, v135
	v_cvt_pk_bf16_f32 v135, v136, v137
	s_nop 2
	ds_write2_b64 v99, v[134:135], v[118:119] offset1:4
	v_cvt_pk_bf16_f32 v118, v126, v127
	v_cvt_pk_bf16_f32 v119, v128, v129
	v_cvt_pk_bf16_f32 v120, v130, v131
	v_cvt_pk_bf16_f32 v121, v132, v133
	v_pk_fma_f32 v[50:51], v[38:39], v[50:51], v[108:109]
	v_pk_fma_f32 v[52:53], v[40:41], v[52:53], v[106:107]
	v_pk_mul_f32 v[106:107], v[34:35], v[116:117]
	v_pk_mul_f32 v[108:109], v[36:37], v[114:115]
	ds_write2_b64 v100, v[118:119], v[120:121] offset1:4
	v_pk_mul_f32 v[118:119], v[34:35], v[124:125]
	v_pk_mul_f32 v[120:121], v[36:37], v[122:123]
	v_pk_fma_f32 v[46:47], v[38:39], v[46:47], v[106:107]
	v_pk_fma_f32 v[48:49], v[40:41], v[48:49], v[108:109]
	v_pk_mul_f32 v[106:107], v[34:35], v[112:113]
	v_pk_mul_f32 v[108:109], v[36:37], v[110:111]
	s_add_i32 s14, s14, 64
	s_sub_i32 s11, s11, 64
	v_pk_fma_f32 v[54:55], v[38:39], v[54:55], v[118:119]
	v_pk_fma_f32 v[56:57], v[40:41], v[56:57], v[120:121]
	v_pk_fma_f32 v[42:43], v[38:39], v[42:43], v[106:107]
	s_cmp_lg_u32 s10, s8
	v_pk_fma_f32 v[44:45], v[40:41], v[44:45], v[108:109]
	s_cbranch_scc0 .LBB0_169
